# EpiKvB epilogue hand-written with in-loop row-scale preload (on top of EpiUq)
# speedup vs baseline: 1.0068x; 1.0016x over previous
.LBB0_354:
	s_add_u32 s0, s42, s72
	s_addc_u32 s63, s43, s73
	s_add_u32 s66, s0, 0x100
	s_addc_u32 s67, s63, 0
	s_and_b64 s[64:65], s[44:45], exec
	s_cselect_b32 s75, s19, s67
	s_cselect_b32 s74, s18, s66
	s_add_u32 s64, s40, s72
	s_addc_u32 s65, s41, s73
	s_add_u32 s64, s64, 0x100
	s_addc_u32 s65, s65, 0
	s_add_i32 s66, 0, 0x10000
	s_and_b64 s[44:45], s[44:45], exec
	s_cselect_b32 s77, s17, s65
	s_cselect_b32 s76, s91, s64
	s_add_i32 s31, 0, 0x14000
	s_add_u32 vcc_lo, s0, 0x30080
	s_addc_u32 vcc_hi, s63, 0
	s_add_i32 s63, s66, s54
	s_add_i32 m0, s34, 0xc000
	s_add_i32 s55, s34, 0xe000
	s_add_i32 s30, s63, 0x2000
	v_add_u32_e32 v0, s66, v148
	s_add_u32 s78, s76, 0x10000
	ds_read_b128 v[130:133], v0
	ds_read_b128 v[144:147], v0 offset:1024
	ds_read_b128 v[150:153], v0 offset:2048
	ds_read_b128 v[154:157], v0 offset:3072
	v_add_u32_e32 v0, s31, v148
	s_addc_u32 s79, s77, 0
	s_add_i32 s67, s31, s54
	ds_read_b128 v[158:161], v0
	ds_read_b128 v[162:165], v0 offset:1024
	ds_read_b128 v[166:169], v0 offset:2048
	ds_read_b128 v[170:173], v0 offset:3072
	s_add_i32 s0, s67, 0x2000
	s_add_i32 s95, 0, 0x18000
	s_add_i32 s94, 0, 0x1c000
	s_add_u32 s72, s74, 0x30000
	s_addc_u32 s73, s75, 0
	s_add_i32 s93, s95, s54
	s_add_i32 s92, s93, 0x2000
	s_add_u32 s44, s76, 0x10080
	s_addc_u32 s45, s77, 0
	s_add_i32 s65, s94, s54
	s_add_i32 s64, s65, 0x2000
	s_cmp_eq_u64 s[38:39], 0
	s_cbranch_scc0 .Lkvb_pa_skip
	s_lshl_b32 s100, s90, 8
	s_add_i32 s100, s100, s82
	v_and_or_b32 v252, v193, 15, s100
	v_bfe_u32 v253, v193, 4, 2
	v_lshlrev_b32_e32 v253, 4, v253
	v_mul_u32_u24_e32 v252, 0x60, v252
	v_add_u32_e32 v252, v252, v253
	global_load_dwordx4 v[194:197], v252, s[10:11]
	global_load_dwordx4 v[198:201], v252, s[10:11] offset:1536
	global_load_dwordx4 v[202:205], v252, s[10:11] offset:3072
	v_add_u32_e32 v253, 0x1200, v252
	global_load_dwordx4 v[206:209], v253, s[10:11]
.Lkvb_pa_skip:
	v_lshl_add_u64 v[134:135], vcc, 0, v[142:143]
	ds_read_b128 v[174:177], v149
	ds_read_b128 v[178:181], v149 offset:1024
	ds_read_b128 v[182:185], v149 offset:2048
	ds_read_b128 v[186:189], v149 offset:3072
	ds_read_b128 v[214:217], v149 offset:4096
	ds_read_b128 v[228:231], v149 offset:5120
	ds_read_b128 v[232:235], v149 offset:6144
	ds_read_b128 v[236:239], v149 offset:7168
	global_load_lds_dwordx4 v[134:135], off
	v_lshl_add_u64 v[134:135], vcc, 0, v[138:139]
	s_mov_b32 m0, s55
	s_nop 0
	global_load_lds_dwordx4 v[134:135], off
	s_waitcnt vmcnt(8)
	s_waitcnt lgkmcnt(0)
	s_barrier
	s_setprio 1
	s_waitcnt lgkmcnt(0)
	v_mfma_f32_16x16x32_bf16 v[126:129], v[130:133], v[174:177], v[126:129]
	v_mfma_f32_16x16x32_bf16 v[122:125], v[150:153], v[174:177], v[122:125]
	v_mfma_f32_16x16x32_bf16 v[110:113], v[130:133], v[182:185], v[110:113]
	v_mfma_f32_16x16x32_bf16 v[106:109], v[150:153], v[182:185], v[106:109]
	v_mfma_f32_16x16x32_bf16 v[94:97], v[130:133], v[214:217], v[94:97]
	v_mfma_f32_16x16x32_bf16 v[90:93], v[150:153], v[214:217], v[90:93]
	v_mfma_f32_16x16x32_bf16 v[78:81], v[130:133], v[232:235], v[78:81]
	v_mfma_f32_16x16x32_bf16 v[74:77], v[150:153], v[232:235], v[74:77]
	v_mfma_f32_16x16x32_bf16 v[126:129], v[144:147], v[178:181], v[126:129]
	v_mfma_f32_16x16x32_bf16 v[122:125], v[154:157], v[178:181], v[122:125]
	v_mfma_f32_16x16x32_bf16 v[110:113], v[144:147], v[186:189], v[110:113]
	v_mfma_f32_16x16x32_bf16 v[106:109], v[154:157], v[186:189], v[106:109]
	v_mfma_f32_16x16x32_bf16 v[94:97], v[144:147], v[228:231], v[94:97]
	v_mfma_f32_16x16x32_bf16 v[90:93], v[154:157], v[228:231], v[90:93]
	v_mfma_f32_16x16x32_bf16 v[78:81], v[144:147], v[236:239], v[78:81]
	v_mfma_f32_16x16x32_bf16 v[74:77], v[154:157], v[236:239], v[74:77]
	s_setprio 0
	s_setprio 1
	v_mfma_f32_16x16x32_bf16 v[118:121], v[158:161], v[174:177], v[118:121]
	v_mfma_f32_16x16x32_bf16 v[114:117], v[166:169], v[174:177], v[114:117]
	v_mfma_f32_16x16x32_bf16 v[102:105], v[158:161], v[182:185], v[102:105]
	v_mfma_f32_16x16x32_bf16 v[98:101], v[166:169], v[182:185], v[98:101]
	v_mfma_f32_16x16x32_bf16 v[86:89], v[158:161], v[214:217], v[86:89]
	v_mfma_f32_16x16x32_bf16 v[82:85], v[166:169], v[214:217], v[82:85]
	v_mfma_f32_16x16x32_bf16 v[70:73], v[158:161], v[232:235], v[70:73]
	v_mfma_f32_16x16x32_bf16 v[66:69], v[166:169], v[232:235], v[66:69]
	v_mfma_f32_16x16x32_bf16 v[118:121], v[162:165], v[178:181], v[118:121]
	v_mfma_f32_16x16x32_bf16 v[114:117], v[170:173], v[178:181], v[114:117]
	v_mfma_f32_16x16x32_bf16 v[102:105], v[162:165], v[186:189], v[102:105]
	v_mfma_f32_16x16x32_bf16 v[98:101], v[170:173], v[186:189], v[98:101]
	v_mfma_f32_16x16x32_bf16 v[86:89], v[162:165], v[228:231], v[86:89]
	v_mfma_f32_16x16x32_bf16 v[82:85], v[170:173], v[228:231], v[82:85]
	v_mfma_f32_16x16x32_bf16 v[70:73], v[162:165], v[236:239], v[70:73]
	v_mfma_f32_16x16x32_bf16 v[66:69], v[170:173], v[236:239], v[66:69]
	s_setprio 0
	s_barrier
	s_mov_b32 m0, s63
	v_lshl_add_u64 v[134:135], s[76:77], 0, v[140:141]
	ds_read_b128 v[174:177], v149 offset:16384
	ds_read_b128 v[178:181], v149 offset:17408
	ds_read_b128 v[182:185], v149 offset:18432
	ds_read_b128 v[186:189], v149 offset:19456
	ds_read_b128 v[214:217], v149 offset:20480
	ds_read_b128 v[228:231], v149 offset:21504
	ds_read_b128 v[232:235], v149 offset:22528
	ds_read_b128 v[236:239], v149 offset:23552
	global_load_lds_dwordx4 v[134:135], off
	v_lshl_add_u64 v[190:191], s[76:77], 0, v[136:137]
	s_mov_b32 m0, s30
	v_lshl_add_u64 v[218:219], s[78:79], 0, v[140:141]
	global_load_lds_dwordx4 v[190:191], off
	s_mov_b32 m0, s67
	v_lshl_add_u64 v[240:241], s[74:75], 0, v[138:139]
	global_load_lds_dwordx4 v[218:219], off
	v_lshl_add_u64 v[218:219], s[78:79], 0, v[136:137]
	s_mov_b32 m0, s0
	s_nop 0
	global_load_lds_dwordx4 v[218:219], off
	v_lshl_add_u64 v[218:219], s[74:75], 0, v[142:143]
	s_mov_b32 m0, s34
	s_nop 0
	global_load_lds_dwordx4 v[218:219], off
	s_mov_b32 m0, s71
	s_nop 0
	global_load_lds_dwordx4 v[240:241], off
	s_waitcnt vmcnt(8)
	s_waitcnt lgkmcnt(0)
	s_barrier
	s_setprio 1
	s_waitcnt lgkmcnt(0)
	v_mfma_f32_16x16x32_bf16 v[62:65], v[130:133], v[174:177], v[62:65]
	v_mfma_f32_16x16x32_bf16 v[58:61], v[150:153], v[174:177], v[58:61]
	v_mfma_f32_16x16x32_bf16 v[46:49], v[130:133], v[182:185], v[46:49]
	v_mfma_f32_16x16x32_bf16 v[42:45], v[150:153], v[182:185], v[42:45]
	v_mfma_f32_16x16x32_bf16 v[30:33], v[130:133], v[214:217], v[30:33]
	v_mfma_f32_16x16x32_bf16 v[26:29], v[150:153], v[214:217], v[26:29]
	v_mfma_f32_16x16x32_bf16 v[14:17], v[130:133], v[232:235], v[14:17]
	v_mfma_f32_16x16x32_bf16 v[10:13], v[150:153], v[232:235], v[10:13]
	v_mfma_f32_16x16x32_bf16 v[62:65], v[144:147], v[178:181], v[62:65]
	v_mfma_f32_16x16x32_bf16 v[58:61], v[154:157], v[178:181], v[58:61]
	v_mfma_f32_16x16x32_bf16 v[46:49], v[144:147], v[186:189], v[46:49]
	v_mfma_f32_16x16x32_bf16 v[42:45], v[154:157], v[186:189], v[42:45]
	v_mfma_f32_16x16x32_bf16 v[30:33], v[144:147], v[228:231], v[30:33]
	v_mfma_f32_16x16x32_bf16 v[26:29], v[154:157], v[228:231], v[26:29]
	v_mfma_f32_16x16x32_bf16 v[14:17], v[144:147], v[236:239], v[14:17]
	v_mfma_f32_16x16x32_bf16 v[10:13], v[154:157], v[236:239], v[10:13]
	s_setprio 0
	s_setprio 1
	v_mfma_f32_16x16x32_bf16 v[54:57], v[158:161], v[174:177], v[54:57]
	v_mfma_f32_16x16x32_bf16 v[50:53], v[166:169], v[174:177], v[50:53]
	v_mfma_f32_16x16x32_bf16 v[38:41], v[158:161], v[182:185], v[38:41]
	v_mfma_f32_16x16x32_bf16 v[34:37], v[166:169], v[182:185], v[34:37]
	v_mfma_f32_16x16x32_bf16 v[22:25], v[158:161], v[214:217], v[22:25]
	v_mfma_f32_16x16x32_bf16 v[18:21], v[166:169], v[214:217], v[18:21]
	v_mfma_f32_16x16x32_bf16 v[6:9], v[158:161], v[232:235], v[6:9]
	v_mfma_f32_16x16x32_bf16 v[2:5], v[166:169], v[232:235], v[2:5]
	v_mfma_f32_16x16x32_bf16 v[54:57], v[162:165], v[178:181], v[54:57]
	v_mfma_f32_16x16x32_bf16 v[50:53], v[170:173], v[178:181], v[50:53]
	v_mfma_f32_16x16x32_bf16 v[38:41], v[162:165], v[186:189], v[38:41]
	v_mfma_f32_16x16x32_bf16 v[34:37], v[170:173], v[186:189], v[34:37]
	v_mfma_f32_16x16x32_bf16 v[22:25], v[162:165], v[228:231], v[22:25]
	v_mfma_f32_16x16x32_bf16 v[18:21], v[170:173], v[228:231], v[18:21]
	v_mfma_f32_16x16x32_bf16 v[6:9], v[162:165], v[236:239], v[6:9]
	v_mfma_f32_16x16x32_bf16 v[2:5], v[170:173], v[236:239], v[2:5]
	s_setprio 0
	s_barrier
	v_add_u32_e32 v0, s95, v148
	ds_read_b128 v[130:133], v0
	ds_read_b128 v[144:147], v0 offset:1024
	ds_read_b128 v[150:153], v0 offset:2048
	ds_read_b128 v[154:157], v0 offset:3072
	v_add_u32_e32 v0, s94, v148
	ds_read_b128 v[158:161], v0
	ds_read_b128 v[162:165], v0 offset:1024
	ds_read_b128 v[166:169], v0 offset:2048
	ds_read_b128 v[170:173], v0 offset:3072
	s_mov_b32 m0, s80
	v_lshl_add_u64 v[242:243], s[72:73], 0, v[142:143]
	ds_read_b128 v[174:177], v149 offset:32768
	ds_read_b128 v[178:181], v149 offset:33792
	ds_read_b128 v[182:185], v149 offset:34816
	ds_read_b128 v[186:189], v149 offset:35840
	ds_read_b128 v[214:217], v149 offset:36864
	ds_read_b128 v[228:231], v149 offset:37888
	ds_read_b128 v[232:235], v149 offset:38912
	ds_read_b128 v[236:239], v149 offset:39936
	s_cmp_eq_u64 s[38:39], 0
	s_cbranch_scc0 .Lkvb_pb_skip
	v_add_f32_e32 v221, v195, v194
	v_add_f32_e32 v253, v196, v197
	v_add_f32_e32 v221, v221, v253
	v_add_f32_e32 v222, v199, v198
	v_add_f32_e32 v253, v200, v201
	v_add_f32_e32 v222, v222, v253
	v_add_f32_e32 v223, v203, v202
	v_add_f32_e32 v253, v204, v205
	v_add_f32_e32 v223, v223, v253
	v_add_f32_e32 v224, v207, v206
	v_add_f32_e32 v253, v208, v209
	v_add_f32_e32 v224, v224, v253
	v_add_u32_e32 v253, 0x3000, v252
	global_load_dwordx4 v[194:197], v253, s[10:11]
	global_load_dwordx4 v[198:201], v253, s[10:11] offset:1536
	global_load_dwordx4 v[202:205], v253, s[10:11] offset:3072
	v_add_u32_e32 v254, 0x4200, v252
	global_load_dwordx4 v[206:209], v254, s[10:11]
.Lkvb_pb_skip:
	global_load_lds_dwordx4 v[242:243], off
	v_lshl_add_u64 v[242:243], s[72:73], 0, v[138:139]
	s_mov_b32 m0, s81
	s_nop 0
	global_load_lds_dwordx4 v[242:243], off
	s_waitcnt vmcnt(8)
	s_waitcnt lgkmcnt(0)
	s_barrier
	s_setprio 1
	s_waitcnt lgkmcnt(0)
	v_mfma_f32_16x16x32_bf16 v[126:129], v[130:133], v[174:177], v[126:129]
	v_mfma_f32_16x16x32_bf16 v[122:125], v[150:153], v[174:177], v[122:125]
	v_mfma_f32_16x16x32_bf16 v[110:113], v[130:133], v[182:185], v[110:113]
	v_mfma_f32_16x16x32_bf16 v[106:109], v[150:153], v[182:185], v[106:109]
	v_mfma_f32_16x16x32_bf16 v[94:97], v[130:133], v[214:217], v[94:97]
	v_mfma_f32_16x16x32_bf16 v[90:93], v[150:153], v[214:217], v[90:93]
	v_mfma_f32_16x16x32_bf16 v[78:81], v[130:133], v[232:235], v[78:81]
	v_mfma_f32_16x16x32_bf16 v[74:77], v[150:153], v[232:235], v[74:77]
	v_mfma_f32_16x16x32_bf16 v[126:129], v[144:147], v[178:181], v[126:129]
	v_mfma_f32_16x16x32_bf16 v[122:125], v[154:157], v[178:181], v[122:125]
	v_mfma_f32_16x16x32_bf16 v[110:113], v[144:147], v[186:189], v[110:113]
	v_mfma_f32_16x16x32_bf16 v[106:109], v[154:157], v[186:189], v[106:109]
	v_mfma_f32_16x16x32_bf16 v[94:97], v[144:147], v[228:231], v[94:97]
	v_mfma_f32_16x16x32_bf16 v[90:93], v[154:157], v[228:231], v[90:93]
	v_mfma_f32_16x16x32_bf16 v[78:81], v[144:147], v[236:239], v[78:81]
	v_mfma_f32_16x16x32_bf16 v[74:77], v[154:157], v[236:239], v[74:77]
	s_setprio 0
	s_setprio 1
	v_mfma_f32_16x16x32_bf16 v[118:121], v[158:161], v[174:177], v[118:121]
	v_mfma_f32_16x16x32_bf16 v[114:117], v[166:169], v[174:177], v[114:117]
	v_mfma_f32_16x16x32_bf16 v[102:105], v[158:161], v[182:185], v[102:105]
	v_mfma_f32_16x16x32_bf16 v[98:101], v[166:169], v[182:185], v[98:101]
	v_mfma_f32_16x16x32_bf16 v[86:89], v[158:161], v[214:217], v[86:89]
	v_mfma_f32_16x16x32_bf16 v[82:85], v[166:169], v[214:217], v[82:85]
	v_mfma_f32_16x16x32_bf16 v[70:73], v[158:161], v[232:235], v[70:73]
	v_mfma_f32_16x16x32_bf16 v[66:69], v[166:169], v[232:235], v[66:69]
	v_mfma_f32_16x16x32_bf16 v[118:121], v[162:165], v[178:181], v[118:121]
	v_mfma_f32_16x16x32_bf16 v[114:117], v[170:173], v[178:181], v[114:117]
	v_mfma_f32_16x16x32_bf16 v[102:105], v[162:165], v[186:189], v[102:105]
	v_mfma_f32_16x16x32_bf16 v[98:101], v[170:173], v[186:189], v[98:101]
	v_mfma_f32_16x16x32_bf16 v[86:89], v[162:165], v[228:231], v[86:89]
	v_mfma_f32_16x16x32_bf16 v[82:85], v[170:173], v[228:231], v[82:85]
	v_mfma_f32_16x16x32_bf16 v[70:73], v[162:165], v[236:239], v[70:73]
	v_mfma_f32_16x16x32_bf16 v[66:69], v[170:173], v[236:239], v[66:69]
	s_setprio 0
	s_barrier
	s_mov_b32 m0, s93
	v_lshl_add_u64 v[134:135], v[134:135], 0, s[52:53]
	ds_read_b128 v[174:177], v149 offset:49152
	ds_read_b128 v[178:181], v149 offset:50176
	ds_read_b128 v[182:185], v149 offset:51200
	ds_read_b128 v[186:189], v149 offset:52224
	ds_read_b128 v[214:217], v149 offset:53248
	ds_read_b128 v[228:231], v149 offset:54272
	ds_read_b128 v[232:235], v149 offset:55296
	ds_read_b128 v[236:239], v149 offset:56320
	global_load_lds_dwordx4 v[134:135], off
	v_lshl_add_u64 v[134:135], v[190:191], 0, s[52:53]
	s_mov_b32 m0, s92
	s_nop 0
	global_load_lds_dwordx4 v[134:135], off
	v_lshl_add_u64 v[134:135], s[44:45], 0, v[140:141]
	s_mov_b32 m0, s65
	s_nop 0
	global_load_lds_dwordx4 v[134:135], off
	v_lshl_add_u64 v[134:135], s[44:45], 0, v[136:137]
	s_mov_b32 m0, s64
	s_nop 0
	global_load_lds_dwordx4 v[134:135], off
	v_lshl_add_u64 v[134:135], v[218:219], 0, s[52:53]
	s_mov_b32 m0, s83
	s_nop 0
	global_load_lds_dwordx4 v[134:135], off
	v_lshl_add_u64 v[134:135], v[240:241], 0, s[52:53]
	s_mov_b32 m0, s84
	s_nop 0
	global_load_lds_dwordx4 v[134:135], off
	s_waitcnt vmcnt(8)
	s_waitcnt lgkmcnt(0)
	s_barrier
	s_setprio 1
	s_waitcnt lgkmcnt(0)
	v_mfma_f32_16x16x32_bf16 v[62:65], v[130:133], v[174:177], v[62:65]
	v_mfma_f32_16x16x32_bf16 v[58:61], v[150:153], v[174:177], v[58:61]
	v_mfma_f32_16x16x32_bf16 v[46:49], v[130:133], v[182:185], v[46:49]
	v_mfma_f32_16x16x32_bf16 v[42:45], v[150:153], v[182:185], v[42:45]
	v_mfma_f32_16x16x32_bf16 v[30:33], v[130:133], v[214:217], v[30:33]
	v_mfma_f32_16x16x32_bf16 v[26:29], v[150:153], v[214:217], v[26:29]
	v_mfma_f32_16x16x32_bf16 v[14:17], v[130:133], v[232:235], v[14:17]
	v_mfma_f32_16x16x32_bf16 v[10:13], v[150:153], v[232:235], v[10:13]
	v_mfma_f32_16x16x32_bf16 v[62:65], v[144:147], v[178:181], v[62:65]
	v_mfma_f32_16x16x32_bf16 v[58:61], v[154:157], v[178:181], v[58:61]
	v_mfma_f32_16x16x32_bf16 v[46:49], v[144:147], v[186:189], v[46:49]
	v_mfma_f32_16x16x32_bf16 v[42:45], v[154:157], v[186:189], v[42:45]
	v_mfma_f32_16x16x32_bf16 v[30:33], v[144:147], v[228:231], v[30:33]
	v_mfma_f32_16x16x32_bf16 v[26:29], v[154:157], v[228:231], v[26:29]
	v_mfma_f32_16x16x32_bf16 v[14:17], v[144:147], v[236:239], v[14:17]
	v_mfma_f32_16x16x32_bf16 v[10:13], v[154:157], v[236:239], v[10:13]
	s_setprio 0
	s_setprio 1
	v_mfma_f32_16x16x32_bf16 v[54:57], v[158:161], v[174:177], v[54:57]
	v_mfma_f32_16x16x32_bf16 v[50:53], v[166:169], v[174:177], v[50:53]
	v_mfma_f32_16x16x32_bf16 v[38:41], v[158:161], v[182:185], v[38:41]
	v_mfma_f32_16x16x32_bf16 v[34:37], v[166:169], v[182:185], v[34:37]
	v_mfma_f32_16x16x32_bf16 v[22:25], v[158:161], v[214:217], v[22:25]
	v_mfma_f32_16x16x32_bf16 v[18:21], v[166:169], v[214:217], v[18:21]
	v_mfma_f32_16x16x32_bf16 v[6:9], v[158:161], v[232:235], v[6:9]
	v_mfma_f32_16x16x32_bf16 v[2:5], v[166:169], v[232:235], v[2:5]
	v_mfma_f32_16x16x32_bf16 v[54:57], v[162:165], v[178:181], v[54:57]
	v_mfma_f32_16x16x32_bf16 v[50:53], v[170:173], v[178:181], v[50:53]
	v_mfma_f32_16x16x32_bf16 v[38:41], v[162:165], v[186:189], v[38:41]
	v_mfma_f32_16x16x32_bf16 v[34:37], v[170:173], v[186:189], v[34:37]
	v_mfma_f32_16x16x32_bf16 v[22:25], v[162:165], v[228:231], v[22:25]
	v_mfma_f32_16x16x32_bf16 v[18:21], v[170:173], v[228:231], v[18:21]
	v_mfma_f32_16x16x32_bf16 v[6:9], v[162:165], v[236:239], v[6:9]
	v_mfma_f32_16x16x32_bf16 v[2:5], v[170:173], v[236:239], v[2:5]
	s_setprio 0
	s_barrier
	s_andn2_b64 vcc, exec, s[38:39]
	s_mov_b64 s[44:45], -1
	s_mov_b64 s[38:39], 0
	s_mov_b64 s[72:73], 0x100
	s_cbranch_vccz .LBB0_354
	s_and_b64 vcc, exec, s[12:13]
	s_cbranch_vccz .LBB0_357
	s_barrier
.LBB0_357:
	s_lshl_b32 s0, s90, 8
	s_add_i32 s0, s0, s82
	v_and_or_b32 v0, v193, 15, s0
	v_bfe_u32 v130, v193, 4, 2
	s_lshr_b32 s17, s0, 11
	v_and_b32_e32 v131, 0x7ff, v0
	s_mov_b32 vcc_lo, -1
	s_mov_b32 vcc_hi, 0
	v_add_f32_e32 v194, v195, v194
	v_add_f32_e32 v196, v196, v197
	v_add_f32_e32 v198, v199, v198
	v_add_f32_e32 v200, v200, v201
	v_add_f32_e32 v202, v203, v202
	v_add_f32_e32 v204, v204, v205
	v_add_f32_e32 v206, v207, v206
	v_add_f32_e32 v208, v208, v209
	v_add_f32_e32 v194, v194, v196
	v_add_f32_e32 v198, v198, v200
	v_add_f32_e32 v202, v202, v204
	v_add_f32_e32 v206, v206, v208
	v_cndmask_b32_e32 v221, 0, v221, vcc
	v_cndmask_b32_e32 v222, 0, v222, vcc
	v_cndmask_b32_e32 v223, 0, v223, vcc
	v_cndmask_b32_e32 v224, 0, v224, vcc
	v_cndmask_b32_e32 v194, 0, v194, vcc
	v_cndmask_b32_e32 v198, 0, v198, vcc
	v_cndmask_b32_e32 v202, 0, v202, vcc
	v_cndmask_b32_e32 v206, 0, v206, vcc
	ds_swizzle_b32 v195, v221 offset:swizzle(SWAP,16)
	ds_swizzle_b32 v196, v222 offset:swizzle(SWAP,16)
	ds_swizzle_b32 v199, v223 offset:swizzle(SWAP,16)
	ds_swizzle_b32 v200, v224 offset:swizzle(SWAP,16)
	ds_swizzle_b32 v203, v194 offset:swizzle(SWAP,16)
	ds_swizzle_b32 v204, v198 offset:swizzle(SWAP,16)
	ds_swizzle_b32 v207, v202 offset:swizzle(SWAP,16)
	ds_swizzle_b32 v208, v206 offset:swizzle(SWAP,16)
	s_waitcnt lgkmcnt(0)
	v_add_f32_e32 v221, v221, v195
	v_add_f32_e32 v222, v222, v196
	v_add_f32_e32 v223, v223, v199
	v_add_f32_e32 v224, v224, v200
	v_add_f32_e32 v194, v194, v203
	v_add_f32_e32 v198, v198, v204
	v_add_f32_e32 v202, v202, v207
	v_add_f32_e32 v206, v206, v208
	v_mov_b32_e32 v197, v221
	v_mov_b32_e32 v201, v222
	v_mov_b32_e32 v205, v223
	v_mov_b32_e32 v209, v224
	v_mov_b32_e32 v240, v194
	v_mov_b32_e32 v241, v198
	v_mov_b32_e32 v242, v202
	v_mov_b32_e32 v243, v206
	v_permlane32_swap_b32_e32 v221, v197
	v_permlane32_swap_b32_e32 v222, v201
	v_permlane32_swap_b32_e32 v223, v205
	v_permlane32_swap_b32_e32 v224, v209
	v_permlane32_swap_b32_e32 v194, v240
	v_permlane32_swap_b32_e32 v198, v241
	v_permlane32_swap_b32_e32 v202, v242
	v_permlane32_swap_b32_e32 v206, v243
	v_add_f32_e32 v221, v221, v197
	v_add_f32_e32 v222, v222, v201
	v_add_f32_e32 v223, v223, v205
	v_add_f32_e32 v224, v224, v209
	v_add_f32_e32 v194, v194, v240
	v_add_f32_e32 v198, v198, v241
	v_add_f32_e32 v202, v202, v242
	v_add_f32_e32 v206, v206, v243
	v_fmamk_f32 v221, v221, 0x3b800000, v192
	v_fmamk_f32 v222, v222, 0x3b800000, v192
	v_fmamk_f32 v223, v223, 0x3b800000, v192
	v_fmamk_f32 v224, v224, 0x3b800000, v192
	v_fmamk_f32 v194, v194, 0x3b800000, v192
	v_fmamk_f32 v198, v198, 0x3b800000, v192
	v_fmamk_f32 v202, v202, 0x3b800000, v192
	v_fmamk_f32 v206, v206, 0x3b800000, v192
	v_rsq_f32_e32 v221, v221
	v_rsq_f32_e32 v222, v222
	v_rsq_f32_e32 v223, v223
	v_rsq_f32_e32 v224, v224
	v_rsq_f32_e32 v194, v194
	v_rsq_f32_e32 v198, v198
	v_rsq_f32_e32 v202, v202
	v_rsq_f32_e32 v206, v206
	v_pk_mul_f32 v[126:127], v[126:127], v[220:221] op_sel:[0,1] op_sel_hi:[1,1]
	v_pk_mul_f32 v[128:129], v[128:129], v[220:221] op_sel:[0,1] op_sel_hi:[1,1]
	v_pk_mul_f32 v[122:123], v[122:123], v[220:221] op_sel:[0,1] op_sel_hi:[1,1]
	v_pk_mul_f32 v[124:125], v[124:125], v[220:221] op_sel:[0,1] op_sel_hi:[1,1]
	v_pk_mul_f32 v[118:119], v[118:119], v[220:221] op_sel:[0,1] op_sel_hi:[1,1]
	v_pk_mul_f32 v[120:121], v[120:121], v[220:221] op_sel:[0,1] op_sel_hi:[1,1]
	v_pk_mul_f32 v[114:115], v[114:115], v[220:221] op_sel:[0,1] op_sel_hi:[1,1]
	v_pk_mul_f32 v[116:117], v[116:117], v[220:221] op_sel:[0,1] op_sel_hi:[1,1]
	v_pk_mul_f32 v[110:111], v[110:111], v[222:223] op_sel_hi:[1,0]
	v_pk_mul_f32 v[112:113], v[112:113], v[222:223] op_sel_hi:[1,0]
	v_pk_mul_f32 v[106:107], v[106:107], v[222:223] op_sel_hi:[1,0]
	v_pk_mul_f32 v[108:109], v[108:109], v[222:223] op_sel_hi:[1,0]
	v_pk_mul_f32 v[102:103], v[102:103], v[222:223] op_sel_hi:[1,0]
	v_pk_mul_f32 v[104:105], v[104:105], v[222:223] op_sel_hi:[1,0]
	v_pk_mul_f32 v[98:99], v[98:99], v[222:223] op_sel_hi:[1,0]
	v_pk_mul_f32 v[100:101], v[100:101], v[222:223] op_sel_hi:[1,0]
	v_pk_mul_f32 v[94:95], v[94:95], v[222:223] op_sel:[0,1] op_sel_hi:[1,1]
	v_pk_mul_f32 v[96:97], v[96:97], v[222:223] op_sel:[0,1] op_sel_hi:[1,1]
	v_pk_mul_f32 v[90:91], v[90:91], v[222:223] op_sel:[0,1] op_sel_hi:[1,1]
	v_pk_mul_f32 v[92:93], v[92:93], v[222:223] op_sel:[0,1] op_sel_hi:[1,1]
	v_pk_mul_f32 v[86:87], v[86:87], v[222:223] op_sel:[0,1] op_sel_hi:[1,1]
	v_pk_mul_f32 v[88:89], v[88:89], v[222:223] op_sel:[0,1] op_sel_hi:[1,1]
	v_pk_mul_f32 v[82:83], v[82:83], v[222:223] op_sel:[0,1] op_sel_hi:[1,1]
	v_pk_mul_f32 v[84:85], v[84:85], v[222:223] op_sel:[0,1] op_sel_hi:[1,1]
	v_pk_mul_f32 v[78:79], v[78:79], v[224:225] op_sel_hi:[1,0]
	v_pk_mul_f32 v[80:81], v[80:81], v[224:225] op_sel_hi:[1,0]
	v_pk_mul_f32 v[74:75], v[74:75], v[224:225] op_sel_hi:[1,0]
	v_pk_mul_f32 v[76:77], v[76:77], v[224:225] op_sel_hi:[1,0]
	v_pk_mul_f32 v[70:71], v[70:71], v[224:225] op_sel_hi:[1,0]
	v_pk_mul_f32 v[72:73], v[72:73], v[224:225] op_sel_hi:[1,0]
	v_pk_mul_f32 v[66:67], v[66:67], v[224:225] op_sel_hi:[1,0]
	v_pk_mul_f32 v[68:69], v[68:69], v[224:225] op_sel_hi:[1,0]
	v_pk_mul_f32 v[62:63], v[62:63], v[194:195] op_sel_hi:[1,0]
	v_pk_mul_f32 v[64:65], v[64:65], v[194:195] op_sel_hi:[1,0]
	v_pk_mul_f32 v[58:59], v[58:59], v[194:195] op_sel_hi:[1,0]
	v_pk_mul_f32 v[60:61], v[60:61], v[194:195] op_sel_hi:[1,0]
	v_pk_mul_f32 v[54:55], v[54:55], v[194:195] op_sel_hi:[1,0]
	v_pk_mul_f32 v[56:57], v[56:57], v[194:195] op_sel_hi:[1,0]
	v_pk_mul_f32 v[50:51], v[50:51], v[194:195] op_sel_hi:[1,0]
	v_pk_mul_f32 v[52:53], v[52:53], v[194:195] op_sel_hi:[1,0]
	v_pk_mul_f32 v[46:47], v[46:47], v[198:199] op_sel_hi:[1,0]
	v_pk_mul_f32 v[48:49], v[48:49], v[198:199] op_sel_hi:[1,0]
	v_pk_mul_f32 v[42:43], v[42:43], v[198:199] op_sel_hi:[1,0]
	v_pk_mul_f32 v[44:45], v[44:45], v[198:199] op_sel_hi:[1,0]
	v_pk_mul_f32 v[38:39], v[38:39], v[198:199] op_sel_hi:[1,0]
	v_pk_mul_f32 v[40:41], v[40:41], v[198:199] op_sel_hi:[1,0]
	v_pk_mul_f32 v[34:35], v[34:35], v[198:199] op_sel_hi:[1,0]
	v_pk_mul_f32 v[36:37], v[36:37], v[198:199] op_sel_hi:[1,0]
	v_pk_mul_f32 v[30:31], v[30:31], v[202:203] op_sel_hi:[1,0]
	v_pk_mul_f32 v[32:33], v[32:33], v[202:203] op_sel_hi:[1,0]
	v_pk_mul_f32 v[26:27], v[26:27], v[202:203] op_sel_hi:[1,0]
	v_pk_mul_f32 v[28:29], v[28:29], v[202:203] op_sel_hi:[1,0]
	v_pk_mul_f32 v[22:23], v[22:23], v[202:203] op_sel_hi:[1,0]
	v_pk_mul_f32 v[24:25], v[24:25], v[202:203] op_sel_hi:[1,0]
	v_pk_mul_f32 v[18:19], v[18:19], v[202:203] op_sel_hi:[1,0]
	v_pk_mul_f32 v[20:21], v[20:21], v[202:203] op_sel_hi:[1,0]
	v_pk_mul_f32 v[14:15], v[14:15], v[206:207] op_sel_hi:[1,0]
	v_pk_mul_f32 v[16:17], v[16:17], v[206:207] op_sel_hi:[1,0]
	v_pk_mul_f32 v[10:11], v[10:11], v[206:207] op_sel_hi:[1,0]
	v_pk_mul_f32 v[12:13], v[12:13], v[206:207] op_sel_hi:[1,0]
	v_pk_mul_f32 v[6:7], v[6:7], v[206:207] op_sel_hi:[1,0]
	v_pk_mul_f32 v[8:9], v[8:9], v[206:207] op_sel_hi:[1,0]
	v_pk_mul_f32 v[2:3], v[2:3], v[206:207] op_sel_hi:[1,0]
	v_pk_mul_f32 v[4:5], v[4:5], v[206:207] op_sel_hi:[1,0]
	s_cmp_lg_u64 s[14:15], 0
	s_cbranch_scc1 .Lkvb_v
	s_lshl_b32 s38, s17, 7
	s_lshl_b32 s39, s89, 4
	s_add_i32 s38, s38, s39
	s_add_i32 s38, s38, s86
	v_add_u32_e32 v144, s38, v130
	v_lshlrev_b32_e32 v144, 15, v144
	v_lshl_add_u32 v132, v131, 4, v144
	v_add_u32_e32 v133, 0x40000, v132
	v_cvt_pk_bf16_f32 v126, v126, v127
	v_cvt_pk_bf16_f32 v127, v128, v129
	v_cvt_pk_bf16_f32 v128, v122, v123
	v_cvt_pk_bf16_f32 v129, v124, v125
	global_store_dwordx4 v132, v[126:129], s[6:7]
	v_cvt_pk_bf16_f32 v118, v118, v119
	v_cvt_pk_bf16_f32 v119, v120, v121
	v_cvt_pk_bf16_f32 v120, v114, v115
	v_cvt_pk_bf16_f32 v121, v116, v117
	global_store_dwordx4 v133, v[118:121], s[6:7]
	v_cvt_pk_bf16_f32 v110, v110, v111
	v_cvt_pk_bf16_f32 v111, v112, v113
	v_cvt_pk_bf16_f32 v112, v106, v107
	v_cvt_pk_bf16_f32 v113, v108, v109
	global_store_dwordx4 v132, v[110:113], s[6:7] offset:256
	v_cvt_pk_bf16_f32 v102, v102, v103
	v_cvt_pk_bf16_f32 v103, v104, v105
	v_cvt_pk_bf16_f32 v104, v98, v99
	v_cvt_pk_bf16_f32 v105, v100, v101
	global_store_dwordx4 v133, v[102:105], s[6:7] offset:256
	v_cvt_pk_bf16_f32 v94, v94, v95
	v_cvt_pk_bf16_f32 v95, v96, v97
	v_cvt_pk_bf16_f32 v96, v90, v91
	v_cvt_pk_bf16_f32 v97, v92, v93
	global_store_dwordx4 v132, v[94:97], s[6:7] offset:512
	v_cvt_pk_bf16_f32 v86, v86, v87
	v_cvt_pk_bf16_f32 v87, v88, v89
	v_cvt_pk_bf16_f32 v88, v82, v83
	v_cvt_pk_bf16_f32 v89, v84, v85
	global_store_dwordx4 v133, v[86:89], s[6:7] offset:512
	v_cvt_pk_bf16_f32 v78, v78, v79
	v_cvt_pk_bf16_f32 v79, v80, v81
	v_cvt_pk_bf16_f32 v80, v74, v75
	v_cvt_pk_bf16_f32 v81, v76, v77
	global_store_dwordx4 v132, v[78:81], s[6:7] offset:768
	v_cvt_pk_bf16_f32 v70, v70, v71
	v_cvt_pk_bf16_f32 v71, v72, v73
	v_cvt_pk_bf16_f32 v72, v66, v67
	v_cvt_pk_bf16_f32 v73, v68, v69
	global_store_dwordx4 v133, v[70:73], s[6:7] offset:768
	v_cvt_pk_bf16_f32 v62, v62, v63
	v_cvt_pk_bf16_f32 v63, v64, v65
	v_cvt_pk_bf16_f32 v64, v58, v59
	v_cvt_pk_bf16_f32 v65, v60, v61
	global_store_dwordx4 v132, v[62:65], s[6:7] offset:2048
	v_cvt_pk_bf16_f32 v54, v54, v55
	v_cvt_pk_bf16_f32 v55, v56, v57
	v_cvt_pk_bf16_f32 v56, v50, v51
	v_cvt_pk_bf16_f32 v57, v52, v53
	global_store_dwordx4 v133, v[54:57], s[6:7] offset:2048
	v_cvt_pk_bf16_f32 v46, v46, v47
	v_cvt_pk_bf16_f32 v47, v48, v49
	v_cvt_pk_bf16_f32 v48, v42, v43
	v_cvt_pk_bf16_f32 v49, v44, v45
	global_store_dwordx4 v132, v[46:49], s[6:7] offset:2304
	v_cvt_pk_bf16_f32 v38, v38, v39
	v_cvt_pk_bf16_f32 v39, v40, v41
	v_cvt_pk_bf16_f32 v40, v34, v35
	v_cvt_pk_bf16_f32 v41, v36, v37
	global_store_dwordx4 v133, v[38:41], s[6:7] offset:2304
	v_cvt_pk_bf16_f32 v30, v30, v31
	v_cvt_pk_bf16_f32 v31, v32, v33
	v_cvt_pk_bf16_f32 v32, v26, v27
	v_cvt_pk_bf16_f32 v33, v28, v29
	global_store_dwordx4 v132, v[30:33], s[6:7] offset:2560
	v_cvt_pk_bf16_f32 v22, v22, v23
	v_cvt_pk_bf16_f32 v23, v24, v25
	v_cvt_pk_bf16_f32 v24, v18, v19
	v_cvt_pk_bf16_f32 v25, v20, v21
	global_store_dwordx4 v133, v[22:25], s[6:7] offset:2560
	v_cvt_pk_bf16_f32 v14, v14, v15
	v_cvt_pk_bf16_f32 v15, v16, v17
	v_cvt_pk_bf16_f32 v16, v10, v11
	v_cvt_pk_bf16_f32 v17, v12, v13
	global_store_dwordx4 v132, v[14:17], s[6:7] offset:2816
	v_cvt_pk_bf16_f32 v6, v6, v7
	v_cvt_pk_bf16_f32 v7, v8, v9
	v_cvt_pk_bf16_f32 v8, v2, v3
	v_cvt_pk_bf16_f32 v9, v4, v5
	global_store_dwordx4 v133, v[6:9], s[6:7] offset:2816
	s_branch .Lkvb_end
.Lkvb_v:
	s_lshl_b32 s38, s17, 5
	s_lshl_b32 s39, s89, 2
	s_add_i32 s38, s38, s39
	s_add_i32 s38, s38, s85
	s_lshl_b32 s38, s38, 17
	v_lshlrev_b32_e32 v144, 4, v130
	v_lshl_add_u32 v144, v131, 6, v144
	v_add_u32_e32 v132, s38, v144
	v_add_u32_e32 v133, 0x40000, v132
	v_add_u32_e32 v134, 0x2000, v132
	v_add_u32_e32 v135, 0x42000, v132
	v_cvt_pk_bf16_f32 v126, v126, v127
	v_cvt_pk_bf16_f32 v127, v128, v129
	v_cvt_pk_bf16_f32 v128, v122, v123
	v_cvt_pk_bf16_f32 v129, v124, v125
	global_store_dwordx4 v132, v[126:129], s[8:9]
	v_cvt_pk_bf16_f32 v118, v118, v119
	v_cvt_pk_bf16_f32 v119, v120, v121
	v_cvt_pk_bf16_f32 v120, v114, v115
	v_cvt_pk_bf16_f32 v121, v116, v117
	global_store_dwordx4 v133, v[118:121], s[8:9]
	v_cvt_pk_bf16_f32 v110, v110, v111
	v_cvt_pk_bf16_f32 v111, v112, v113
	v_cvt_pk_bf16_f32 v112, v106, v107
	v_cvt_pk_bf16_f32 v113, v108, v109
	global_store_dwordx4 v132, v[110:113], s[8:9] offset:1024
	v_cvt_pk_bf16_f32 v102, v102, v103
	v_cvt_pk_bf16_f32 v103, v104, v105
	v_cvt_pk_bf16_f32 v104, v98, v99
	v_cvt_pk_bf16_f32 v105, v100, v101
	global_store_dwordx4 v133, v[102:105], s[8:9] offset:1024
	v_cvt_pk_bf16_f32 v94, v94, v95
	v_cvt_pk_bf16_f32 v95, v96, v97
	v_cvt_pk_bf16_f32 v96, v90, v91
	v_cvt_pk_bf16_f32 v97, v92, v93
	global_store_dwordx4 v132, v[94:97], s[8:9] offset:2048
	v_cvt_pk_bf16_f32 v86, v86, v87
	v_cvt_pk_bf16_f32 v87, v88, v89
	v_cvt_pk_bf16_f32 v88, v82, v83
	v_cvt_pk_bf16_f32 v89, v84, v85
	global_store_dwordx4 v133, v[86:89], s[8:9] offset:2048
	v_cvt_pk_bf16_f32 v78, v78, v79
	v_cvt_pk_bf16_f32 v79, v80, v81
	v_cvt_pk_bf16_f32 v80, v74, v75
	v_cvt_pk_bf16_f32 v81, v76, v77
	global_store_dwordx4 v132, v[78:81], s[8:9] offset:3072
	v_cvt_pk_bf16_f32 v70, v70, v71
	v_cvt_pk_bf16_f32 v71, v72, v73
	v_cvt_pk_bf16_f32 v72, v66, v67
	v_cvt_pk_bf16_f32 v73, v68, v69
	global_store_dwordx4 v133, v[70:73], s[8:9] offset:3072
	v_cvt_pk_bf16_f32 v62, v62, v63
	v_cvt_pk_bf16_f32 v63, v64, v65
	v_cvt_pk_bf16_f32 v64, v58, v59
	v_cvt_pk_bf16_f32 v65, v60, v61
	global_store_dwordx4 v134, v[62:65], s[8:9]
	v_cvt_pk_bf16_f32 v54, v54, v55
	v_cvt_pk_bf16_f32 v55, v56, v57
	v_cvt_pk_bf16_f32 v56, v50, v51
	v_cvt_pk_bf16_f32 v57, v52, v53
	global_store_dwordx4 v135, v[54:57], s[8:9]
	v_cvt_pk_bf16_f32 v46, v46, v47
	v_cvt_pk_bf16_f32 v47, v48, v49
	v_cvt_pk_bf16_f32 v48, v42, v43
	v_cvt_pk_bf16_f32 v49, v44, v45
	global_store_dwordx4 v134, v[46:49], s[8:9] offset:1024
	v_cvt_pk_bf16_f32 v38, v38, v39
	v_cvt_pk_bf16_f32 v39, v40, v41
	v_cvt_pk_bf16_f32 v40, v34, v35
	v_cvt_pk_bf16_f32 v41, v36, v37
	global_store_dwordx4 v135, v[38:41], s[8:9] offset:1024
	v_cvt_pk_bf16_f32 v30, v30, v31
	v_cvt_pk_bf16_f32 v31, v32, v33
	v_cvt_pk_bf16_f32 v32, v26, v27
	v_cvt_pk_bf16_f32 v33, v28, v29
	global_store_dwordx4 v134, v[30:33], s[8:9] offset:2048
	v_cvt_pk_bf16_f32 v22, v22, v23
	v_cvt_pk_bf16_f32 v23, v24, v25
	v_cvt_pk_bf16_f32 v24, v18, v19
	v_cvt_pk_bf16_f32 v25, v20, v21
	global_store_dwordx4 v135, v[22:25], s[8:9] offset:2048
	v_cvt_pk_bf16_f32 v14, v14, v15
	v_cvt_pk_bf16_f32 v15, v16, v17
	v_cvt_pk_bf16_f32 v16, v10, v11
	v_cvt_pk_bf16_f32 v17, v12, v13
	global_store_dwordx4 v134, v[14:17], s[8:9] offset:3072
	v_cvt_pk_bf16_f32 v6, v6, v7
	v_cvt_pk_bf16_f32 v7, v8, v9
	v_cvt_pk_bf16_f32 v8, v2, v3
	v_cvt_pk_bf16_f32 v9, v4, v5
	global_store_dwordx4 v135, v[6:9], s[8:9] offset:3072
.Lkvb_end:
	v_readlane_b32 s66, v250, 27
	v_readlane_b32 s92, v248, 24
	v_readlane_b32 s67, v250, 28
	v_readlane_b32 s93, v248, 25
	v_mov_b64_e32 v[194:195], 0xc0
	v_mov_b64_e32 v[196:197], 0xbf
	v_mov_b64_e32 v[198:199], 0x180
	v_mov_b64_e32 v[200:201], 0x17f
	v_mov_b64_e32 v[202:203], 0x200
	v_mov_b64_e32 v[204:205], 0x1ff
	v_mov_b64_e32 v[206:207], 0x100
	v_mov_b64_e32 v[208:209], 0xff
	v_mov_b32_e32 v221, 0x3e38aa3b
	v_mov_b32_e32 v222, 0x7c
	v_mov_b32_e32 v223, 0x80
	v_mov_b32_e32 v224, 0x42800000
	s_and_b64 vcc, exec, s[36:37]
	s_mov_b64 s[36:37], -1
	s_cbranch_vccnz .LBB0_344
	s_andn2_b64 vcc, exec, s[2:3]
	s_cbranch_vccnz .LBB0_343
	s_barrier
	s_branch .LBB0_343
